# P9 K-loop: one iteration before the end wave 1 warms the 8 KiB of the fused final-norm epilogue code, stacked on v93
# baseline (speedup 1.0000x reference)
.LBB0_2129:
	ds_read_b128 v[132:135], v223
	ds_read_b128 v[136:139], v223 offset:1024
	ds_read_b128 v[140:143], v223 offset:2048
	ds_read_b128 v[144:147], v223 offset:3072
	ds_read_b128 v[148:151], v224
	ds_read_b128 v[152:155], v224 offset:1024
	ds_read_b128 v[156:159], v224 offset:2048
	ds_read_b128 v[160:163], v224 offset:3072
	s_add_u32 s84, s58, 0xfff50080
	s_addc_u32 s85, s59, -1
	s_cmp_eq_u32 s74, s67
	s_cselect_b32 vcc_hi, s35, s85
	s_cselect_b32 vcc_lo, s34, s84
	s_cselect_b32 s85, s39, s37
	s_cselect_b32 s84, s38, s36
	s_mov_b32 m0, s17
	v_lshl_add_u64 v[192:193], s[58:59], 0, v[198:199]
	ds_read_b128 v[164:167], v225
	ds_read_b128 v[168:171], v225 offset:1024
	ds_read_b128 v[172:175], v225 offset:2048
	ds_read_b128 v[176:179], v225 offset:3072
	ds_read_b128 v[180:183], v225 offset:4096
	ds_read_b128 v[184:187], v225 offset:5120
	ds_read_b128 v[188:191], v225 offset:6144
	ds_read_b128 v[200:203], v225 offset:7168
	global_load_lds_dwordx4 v[192:193], off
	v_lshl_add_u64 v[192:193], v[192:193], 0, s[18:19]
	s_mov_b32 m0, s40
	s_nop 0
	global_load_lds_dwordx4 v[192:193], off
	s_waitcnt vmcnt(8)
	s_waitcnt lgkmcnt(0)
	s_waitcnt lgkmcnt(0)
	v_mfma_f32_16x16x32_bf16 v[126:129], v[132:135], v[164:167], v[126:129]
	v_mfma_f32_16x16x32_bf16 v[122:125], v[140:143], v[164:167], v[122:125]
	s_barrier
	s_setprio 1
	v_mfma_f32_16x16x32_bf16 v[110:113], v[132:135], v[172:175], v[110:113]
	v_mfma_f32_16x16x32_bf16 v[106:109], v[140:143], v[172:175], v[106:109]
	v_mfma_f32_16x16x32_bf16 v[94:97], v[132:135], v[180:183], v[94:97]
	v_mfma_f32_16x16x32_bf16 v[90:93], v[140:143], v[180:183], v[90:93]
	v_mfma_f32_16x16x32_bf16 v[78:81], v[132:135], v[188:191], v[78:81]
	v_mfma_f32_16x16x32_bf16 v[74:77], v[140:143], v[188:191], v[74:77]
	v_mfma_f32_16x16x32_bf16 v[126:129], v[136:139], v[168:171], v[126:129]
	v_mfma_f32_16x16x32_bf16 v[122:125], v[144:147], v[168:171], v[122:125]
	v_mfma_f32_16x16x32_bf16 v[110:113], v[136:139], v[176:179], v[110:113]
	v_mfma_f32_16x16x32_bf16 v[106:109], v[144:147], v[176:179], v[106:109]
	v_mfma_f32_16x16x32_bf16 v[94:97], v[136:139], v[184:187], v[94:97]
	v_mfma_f32_16x16x32_bf16 v[90:93], v[144:147], v[184:187], v[90:93]
	v_mfma_f32_16x16x32_bf16 v[78:81], v[136:139], v[200:203], v[78:81]
	v_mfma_f32_16x16x32_bf16 v[74:77], v[144:147], v[200:203], v[74:77]
	s_setprio 0
	s_setprio 1
	v_mfma_f32_16x16x32_bf16 v[118:121], v[148:151], v[164:167], v[118:121]
	v_mfma_f32_16x16x32_bf16 v[114:117], v[156:159], v[164:167], v[114:117]
	v_mfma_f32_16x16x32_bf16 v[102:105], v[148:151], v[172:175], v[102:105]
	v_mfma_f32_16x16x32_bf16 v[98:101], v[156:159], v[172:175], v[98:101]
	v_mfma_f32_16x16x32_bf16 v[86:89], v[148:151], v[180:183], v[86:89]
	v_mfma_f32_16x16x32_bf16 v[82:85], v[156:159], v[180:183], v[82:85]
	v_mfma_f32_16x16x32_bf16 v[70:73], v[148:151], v[188:191], v[70:73]
	v_mfma_f32_16x16x32_bf16 v[62:65], v[156:159], v[188:191], v[62:65]
	v_mfma_f32_16x16x32_bf16 v[118:121], v[152:155], v[168:171], v[118:121]
	v_mfma_f32_16x16x32_bf16 v[114:117], v[160:163], v[168:171], v[114:117]
	v_mfma_f32_16x16x32_bf16 v[102:105], v[152:155], v[176:179], v[102:105]
	v_mfma_f32_16x16x32_bf16 v[98:101], v[160:163], v[176:179], v[98:101]
	v_mfma_f32_16x16x32_bf16 v[86:89], v[152:155], v[184:187], v[86:89]
	v_mfma_f32_16x16x32_bf16 v[82:85], v[160:163], v[184:187], v[82:85]
	v_mfma_f32_16x16x32_bf16 v[70:73], v[152:155], v[200:203], v[70:73]
	v_mfma_f32_16x16x32_bf16 v[62:65], v[160:163], v[200:203], v[62:65]
	s_setprio 0
	s_barrier
	s_mov_b32 m0, s60
	v_lshl_add_u64 v[192:193], s[84:85], 0, v[196:197]
	ds_read_b128 v[164:167], v225 offset:16384
	ds_read_b128 v[168:171], v225 offset:17408
	ds_read_b128 v[172:175], v225 offset:18432
	ds_read_b128 v[176:179], v225 offset:19456
	ds_read_b128 v[180:183], v225 offset:20480
	ds_read_b128 v[184:187], v225 offset:21504
	ds_read_b128 v[188:191], v225 offset:22528
	ds_read_b128 v[200:203], v225 offset:23552
	global_load_lds_dwordx4 v[192:193], off
	v_lshl_add_u64 v[204:205], v[192:193], 0, s[18:19]
	s_mov_b32 m0, s61
	s_nop 0
	global_load_lds_dwordx4 v[204:205], off
	v_lshl_add_u64 v[204:205], v[192:193], 0, s[22:23]
	s_mov_b32 m0, s62
	s_nop 0
	global_load_lds_dwordx4 v[204:205], off
	v_lshl_add_u64 v[204:205], v[192:193], 0, s[24:25]
	s_mov_b32 m0, s63
	s_nop 0
	global_load_lds_dwordx4 v[204:205], off
	v_lshl_add_u64 v[204:205], vcc, 0, v[194:195]
	s_mov_b32 m0, s78
	v_lshl_add_u64 v[206:207], v[204:205], 0, s[18:19]
	global_load_lds_dwordx4 v[204:205], off
	s_mov_b32 m0, s79
	s_nop 0
	global_load_lds_dwordx4 v[206:207], off
	s_waitcnt vmcnt(8)
	s_waitcnt lgkmcnt(0)
	s_waitcnt lgkmcnt(0)
	v_mfma_f32_16x16x32_bf16 v[66:69], v[132:135], v[164:167], v[66:69]
	v_mfma_f32_16x16x32_bf16 v[58:61], v[140:143], v[164:167], v[58:61]
	s_barrier
	s_setprio 1
	v_mfma_f32_16x16x32_bf16 v[46:49], v[132:135], v[172:175], v[46:49]
	v_mfma_f32_16x16x32_bf16 v[42:45], v[140:143], v[172:175], v[42:45]
	v_mfma_f32_16x16x32_bf16 v[30:33], v[132:135], v[180:183], v[30:33]
	v_mfma_f32_16x16x32_bf16 v[26:29], v[140:143], v[180:183], v[26:29]
	v_mfma_f32_16x16x32_bf16 v[14:17], v[132:135], v[188:191], v[14:17]
	v_mfma_f32_16x16x32_bf16 v[10:13], v[140:143], v[188:191], v[10:13]
	v_mfma_f32_16x16x32_bf16 v[66:69], v[136:139], v[168:171], v[66:69]
	v_mfma_f32_16x16x32_bf16 v[58:61], v[144:147], v[168:171], v[58:61]
	v_mfma_f32_16x16x32_bf16 v[46:49], v[136:139], v[176:179], v[46:49]
	v_mfma_f32_16x16x32_bf16 v[42:45], v[144:147], v[176:179], v[42:45]
	v_mfma_f32_16x16x32_bf16 v[30:33], v[136:139], v[184:187], v[30:33]
	v_mfma_f32_16x16x32_bf16 v[26:29], v[144:147], v[184:187], v[26:29]
	v_mfma_f32_16x16x32_bf16 v[14:17], v[136:139], v[200:203], v[14:17]
	v_mfma_f32_16x16x32_bf16 v[10:13], v[144:147], v[200:203], v[10:13]
	s_setprio 0
	s_setprio 1
	v_mfma_f32_16x16x32_bf16 v[54:57], v[148:151], v[164:167], v[54:57]
	v_mfma_f32_16x16x32_bf16 v[50:53], v[156:159], v[164:167], v[50:53]
	v_mfma_f32_16x16x32_bf16 v[38:41], v[148:151], v[172:175], v[38:41]
	v_mfma_f32_16x16x32_bf16 v[34:37], v[156:159], v[172:175], v[34:37]
	v_mfma_f32_16x16x32_bf16 v[22:25], v[148:151], v[180:183], v[22:25]
	v_mfma_f32_16x16x32_bf16 v[18:21], v[156:159], v[180:183], v[18:21]
	v_mfma_f32_16x16x32_bf16 v[6:9], v[148:151], v[188:191], v[6:9]
	v_mfma_f32_16x16x32_bf16 v[2:5], v[156:159], v[188:191], v[2:5]
	v_mfma_f32_16x16x32_bf16 v[54:57], v[152:155], v[168:171], v[54:57]
	v_mfma_f32_16x16x32_bf16 v[50:53], v[160:163], v[168:171], v[50:53]
	v_mfma_f32_16x16x32_bf16 v[38:41], v[152:155], v[176:179], v[38:41]
	v_mfma_f32_16x16x32_bf16 v[34:37], v[160:163], v[176:179], v[34:37]
	v_mfma_f32_16x16x32_bf16 v[22:25], v[152:155], v[184:187], v[22:25]
	v_mfma_f32_16x16x32_bf16 v[18:21], v[160:163], v[184:187], v[18:21]
	v_mfma_f32_16x16x32_bf16 v[6:9], v[152:155], v[200:203], v[6:9]
	v_mfma_f32_16x16x32_bf16 v[2:5], v[160:163], v[200:203], v[2:5]
	s_setprio 0
	s_barrier
	ds_read_b128 v[132:135], v130
	ds_read_b128 v[136:139], v130 offset:1024
	ds_read_b128 v[140:143], v130 offset:2048
	ds_read_b128 v[144:147], v130 offset:3072
	ds_read_b128 v[148:151], v131
	ds_read_b128 v[152:155], v131 offset:1024
	ds_read_b128 v[156:159], v131 offset:2048
	ds_read_b128 v[160:163], v131 offset:3072
	s_mov_b32 m0, s80
	v_lshl_add_u64 v[206:207], v[204:205], 0, s[22:23]
	ds_read_b128 v[164:167], v225 offset:32768
	ds_read_b128 v[168:171], v225 offset:33792
	ds_read_b128 v[172:175], v225 offset:34816
	ds_read_b128 v[176:179], v225 offset:35840
	ds_read_b128 v[180:183], v225 offset:36864
	ds_read_b128 v[184:187], v225 offset:37888
	ds_read_b128 v[188:191], v225 offset:38912
	ds_read_b128 v[200:203], v225 offset:39936
	global_load_lds_dwordx4 v[206:207], off
	v_lshl_add_u64 v[206:207], v[204:205], 0, s[24:25]
	s_mov_b32 m0, s81
	s_nop 0
	global_load_lds_dwordx4 v[206:207], off
	s_waitcnt vmcnt(8)
	s_waitcnt lgkmcnt(0)
	s_waitcnt lgkmcnt(0)
	v_mfma_f32_16x16x32_bf16 v[126:129], v[132:135], v[164:167], v[126:129]
	v_mfma_f32_16x16x32_bf16 v[122:125], v[140:143], v[164:167], v[122:125]
	s_barrier
	s_setprio 1
	v_mfma_f32_16x16x32_bf16 v[110:113], v[132:135], v[172:175], v[110:113]
	v_mfma_f32_16x16x32_bf16 v[106:109], v[140:143], v[172:175], v[106:109]
	v_mfma_f32_16x16x32_bf16 v[94:97], v[132:135], v[180:183], v[94:97]
	v_mfma_f32_16x16x32_bf16 v[90:93], v[140:143], v[180:183], v[90:93]
	v_mfma_f32_16x16x32_bf16 v[78:81], v[132:135], v[188:191], v[78:81]
	v_mfma_f32_16x16x32_bf16 v[74:77], v[140:143], v[188:191], v[74:77]
	v_mfma_f32_16x16x32_bf16 v[126:129], v[136:139], v[168:171], v[126:129]
	v_mfma_f32_16x16x32_bf16 v[122:125], v[144:147], v[168:171], v[122:125]
	v_mfma_f32_16x16x32_bf16 v[110:113], v[136:139], v[176:179], v[110:113]
	v_mfma_f32_16x16x32_bf16 v[106:109], v[144:147], v[176:179], v[106:109]
	v_mfma_f32_16x16x32_bf16 v[94:97], v[136:139], v[184:187], v[94:97]
	v_mfma_f32_16x16x32_bf16 v[90:93], v[144:147], v[184:187], v[90:93]
	v_mfma_f32_16x16x32_bf16 v[78:81], v[136:139], v[200:203], v[78:81]
	v_mfma_f32_16x16x32_bf16 v[74:77], v[144:147], v[200:203], v[74:77]
	s_setprio 0
	s_setprio 1
	v_mfma_f32_16x16x32_bf16 v[118:121], v[148:151], v[164:167], v[118:121]
	v_mfma_f32_16x16x32_bf16 v[114:117], v[156:159], v[164:167], v[114:117]
	v_mfma_f32_16x16x32_bf16 v[102:105], v[148:151], v[172:175], v[102:105]
	v_mfma_f32_16x16x32_bf16 v[98:101], v[156:159], v[172:175], v[98:101]
	v_mfma_f32_16x16x32_bf16 v[86:89], v[148:151], v[180:183], v[86:89]
	v_mfma_f32_16x16x32_bf16 v[82:85], v[156:159], v[180:183], v[82:85]
	v_mfma_f32_16x16x32_bf16 v[70:73], v[148:151], v[188:191], v[70:73]
	v_mfma_f32_16x16x32_bf16 v[62:65], v[156:159], v[188:191], v[62:65]
	v_mfma_f32_16x16x32_bf16 v[118:121], v[152:155], v[168:171], v[118:121]
	v_mfma_f32_16x16x32_bf16 v[114:117], v[160:163], v[168:171], v[114:117]
	v_mfma_f32_16x16x32_bf16 v[102:105], v[152:155], v[176:179], v[102:105]
	v_mfma_f32_16x16x32_bf16 v[98:101], v[160:163], v[176:179], v[98:101]
	v_mfma_f32_16x16x32_bf16 v[86:89], v[152:155], v[184:187], v[86:89]
	v_mfma_f32_16x16x32_bf16 v[82:85], v[160:163], v[184:187], v[82:85]
	v_mfma_f32_16x16x32_bf16 v[70:73], v[152:155], v[200:203], v[70:73]
	v_mfma_f32_16x16x32_bf16 v[62:65], v[160:163], v[200:203], v[62:65]
	s_setprio 0
	s_barrier
	s_mov_b32 m0, s33
	v_lshl_add_u64 v[206:207], v[192:193], 0, s[46:47]
	ds_read_b128 v[164:167], v225 offset:49152
	ds_read_b128 v[168:171], v225 offset:50176
	ds_read_b128 v[172:175], v225 offset:51200
	ds_read_b128 v[176:179], v225 offset:52224
	ds_read_b128 v[180:183], v225 offset:53248
	ds_read_b128 v[184:187], v225 offset:54272
	ds_read_b128 v[188:191], v225 offset:55296
	ds_read_b128 v[200:203], v225 offset:56320
	global_load_lds_dwordx4 v[206:207], off
	v_lshl_add_u64 v[206:207], v[192:193], 0, s[48:49]
	s_mov_b32 m0, s64
	s_nop 0
	global_load_lds_dwordx4 v[206:207], off
	v_lshl_add_u64 v[206:207], v[192:193], 0, s[50:51]
	s_mov_b32 m0, s65
	v_lshl_add_u64 v[192:193], v[192:193], 0, s[52:53]
	global_load_lds_dwordx4 v[206:207], off
	s_mov_b32 m0, s66
	s_nop 0
	global_load_lds_dwordx4 v[192:193], off
	v_lshl_add_u64 v[192:193], v[204:205], 0, s[46:47]
	s_mov_b32 m0, s90
	s_nop 0
	global_load_lds_dwordx4 v[192:193], off
	v_lshl_add_u64 v[192:193], v[204:205], 0, s[48:49]
	s_mov_b32 m0, s91
	s_nop 0
	global_load_lds_dwordx4 v[192:193], off
	s_waitcnt vmcnt(8)
	s_waitcnt lgkmcnt(0)
	s_waitcnt lgkmcnt(0)
	v_mfma_f32_16x16x32_bf16 v[66:69], v[132:135], v[164:167], v[66:69]
	v_mfma_f32_16x16x32_bf16 v[58:61], v[140:143], v[164:167], v[58:61]
	s_barrier
	s_setprio 1
	v_mfma_f32_16x16x32_bf16 v[46:49], v[132:135], v[172:175], v[46:49]
	v_mfma_f32_16x16x32_bf16 v[42:45], v[140:143], v[172:175], v[42:45]
	v_mfma_f32_16x16x32_bf16 v[30:33], v[132:135], v[180:183], v[30:33]
	v_mfma_f32_16x16x32_bf16 v[26:29], v[140:143], v[180:183], v[26:29]
	v_mfma_f32_16x16x32_bf16 v[14:17], v[132:135], v[188:191], v[14:17]
	v_mfma_f32_16x16x32_bf16 v[10:13], v[140:143], v[188:191], v[10:13]
	v_mfma_f32_16x16x32_bf16 v[66:69], v[136:139], v[168:171], v[66:69]
	v_mfma_f32_16x16x32_bf16 v[58:61], v[144:147], v[168:171], v[58:61]
	v_mfma_f32_16x16x32_bf16 v[46:49], v[136:139], v[176:179], v[46:49]
	v_mfma_f32_16x16x32_bf16 v[42:45], v[144:147], v[176:179], v[42:45]
	v_mfma_f32_16x16x32_bf16 v[30:33], v[136:139], v[184:187], v[30:33]
	v_mfma_f32_16x16x32_bf16 v[26:29], v[144:147], v[184:187], v[26:29]
	v_mfma_f32_16x16x32_bf16 v[14:17], v[136:139], v[200:203], v[14:17]
	v_mfma_f32_16x16x32_bf16 v[10:13], v[144:147], v[200:203], v[10:13]
	s_setprio 0
	s_setprio 1
	v_mfma_f32_16x16x32_bf16 v[54:57], v[148:151], v[164:167], v[54:57]
	v_mfma_f32_16x16x32_bf16 v[50:53], v[156:159], v[164:167], v[50:53]
	v_mfma_f32_16x16x32_bf16 v[38:41], v[148:151], v[172:175], v[38:41]
	v_mfma_f32_16x16x32_bf16 v[34:37], v[156:159], v[172:175], v[34:37]
	v_mfma_f32_16x16x32_bf16 v[22:25], v[148:151], v[180:183], v[22:25]
	v_mfma_f32_16x16x32_bf16 v[18:21], v[156:159], v[180:183], v[18:21]
	v_mfma_f32_16x16x32_bf16 v[6:9], v[148:151], v[188:191], v[6:9]
	v_mfma_f32_16x16x32_bf16 v[2:5], v[156:159], v[188:191], v[2:5]
	v_mfma_f32_16x16x32_bf16 v[54:57], v[152:155], v[168:171], v[54:57]
	v_mfma_f32_16x16x32_bf16 v[50:53], v[160:163], v[168:171], v[50:53]
	v_mfma_f32_16x16x32_bf16 v[38:41], v[152:155], v[176:179], v[38:41]
	v_mfma_f32_16x16x32_bf16 v[34:37], v[160:163], v[176:179], v[34:37]
	v_mfma_f32_16x16x32_bf16 v[22:25], v[152:155], v[184:187], v[22:25]
	v_mfma_f32_16x16x32_bf16 v[18:21], v[160:163], v[184:187], v[18:21]
	v_mfma_f32_16x16x32_bf16 v[6:9], v[152:155], v[200:203], v[6:9]
	v_mfma_f32_16x16x32_bf16 v[2:5], v[160:163], v[200:203], v[2:5]
	s_setprio 0
	s_barrier
	s_add_i32 s84, s67, 2
	s_add_u32 s58, s58, 0x100
	s_addc_u32 s59, s59, 0
	s_add_u32 s36, s36, 0x100
	s_addc_u32 s37, s37, 0
	s_sub_i32 s98, s74, s67
	s_cmp_lg_u32 s98, 2
	s_cbranch_scc1 .Lcpf_skip_f
	v_readlane_b32 s98, v254, 61
	s_cmp_lg_u32 s98, 1
	s_cbranch_scc1 .Lcpf_skip_f
	s_getpc_b64 s[98:99]
.Lcpf_pc_f:
	s_add_u32 s98, s98, .LBB0_2164-.Lcpf_pc_f
	s_addc_u32 s99, s99, 0
	v_mbcnt_lo_u32_b32 v252, -1, 0
	v_mbcnt_hi_u32_b32 v252, -1, v252
	v_lshlrev_b32_e32 v252, 7, v252
	global_load_dword v253, v252, s[98:99]
.Lcpf_skip_f:
	s_cmp_ge_i32 s67, s74
	s_mov_b32 s67, s84
	s_cbranch_scc0 .LBB0_2129
